# K loop: six back-to-back duplicate lgkmcnt(0) waits removed (on top of the static priority raise)
# baseline (speedup 1.0000x reference)
.Lprio_lo:
.LBB0_588:
	s_add_i32 s10, 0, 0x10000
	v_add_u32_e32 v148, s10, v184
	s_waitcnt lgkmcnt(0)
	ds_read_b128 v[136:139], v148
	ds_read_b128 v[140:143], v148 offset:1024
	ds_read_b128 v[144:147], v148 offset:2048
	ds_read_b128 v[148:151], v148 offset:3072
	s_add_i32 s9, s8, 2
	s_cmp_eq_u32 s2, s8
	v_lshl_add_u64 v[154:155], v[130:131], 0, s[54:55]
	s_cselect_b64 vcc, -1, 0
	v_cndmask_b32_e32 v155, v155, v132, vcc
	v_cndmask_b32_e32 v154, v154, v133, vcc
	v_cndmask_b32_e32 v211, v129, v134, vcc
	v_cndmask_b32_e32 v210, v128, v135, vcc
	v_lshl_add_u64 v[214:215], v[130:131], 0, v[162:163]
	s_add_i32 m0, s28, 0xc000
	ds_read_b128 v[172:175], v185
	ds_read_b128 v[176:179], v185 offset:1024
	ds_read_b128 v[180:183], v185 offset:2048
	ds_read_b128 v[186:189], v185 offset:3072
	ds_read_b128 v[190:193], v185 offset:4096
	ds_read_b128 v[194:197], v185 offset:5120
	ds_read_b128 v[198:201], v185 offset:6144
	ds_read_b128 v[202:205], v185 offset:7168
	global_load_lds_dwordx4 v[214:215], off
	v_lshl_add_u64 v[214:215], v[130:131], 0, v[160:161]
	s_add_i32 m0, s28, 0xe000
	s_nop 0
	global_load_lds_dwordx4 v[214:215], off
	s_waitcnt lgkmcnt(8)
	s_barrier
	s_waitcnt lgkmcnt(0)
	v_mfma_f32_16x16x32_bf16 v[124:127], v[136:139], v[172:175], v[124:127]
	v_mfma_f32_16x16x32_bf16 v[120:123], v[144:147], v[172:175], v[120:123]
	v_mfma_f32_16x16x32_bf16 v[108:111], v[136:139], v[180:183], v[108:111]
	v_mfma_f32_16x16x32_bf16 v[104:107], v[144:147], v[180:183], v[104:107]
	v_mfma_f32_16x16x32_bf16 v[92:95], v[136:139], v[190:193], v[92:95]
	v_mfma_f32_16x16x32_bf16 v[88:91], v[144:147], v[190:193], v[88:91]
	v_mfma_f32_16x16x32_bf16 v[76:79], v[136:139], v[198:201], v[76:79]
	v_mfma_f32_16x16x32_bf16 v[72:75], v[144:147], v[198:201], v[72:75]
	v_mfma_f32_16x16x32_bf16 v[124:127], v[140:143], v[176:179], v[124:127]
	v_mfma_f32_16x16x32_bf16 v[120:123], v[148:151], v[176:179], v[120:123]
	v_mfma_f32_16x16x32_bf16 v[108:111], v[140:143], v[186:189], v[108:111]
	v_mfma_f32_16x16x32_bf16 v[104:107], v[148:151], v[186:189], v[104:107]
	v_mfma_f32_16x16x32_bf16 v[92:95], v[140:143], v[194:197], v[92:95]
	v_mfma_f32_16x16x32_bf16 v[88:91], v[148:151], v[194:197], v[88:91]
	v_mfma_f32_16x16x32_bf16 v[76:79], v[140:143], v[202:205], v[76:79]
	v_mfma_f32_16x16x32_bf16 v[72:75], v[148:151], v[202:205], v[72:75]
	s_barrier
	s_add_i32 s8, 0, 0x14000
	s_add_i32 s10, s10, s71
	v_add_u32_e32 v152, s8, v184
	v_lshl_add_u64 v[214:215], v[210:211], 0, v[156:157]
	s_mov_b32 m0, s10
	ds_read_b128 v[226:229], v152
	ds_read_b128 v[230:233], v152 offset:1024
	ds_read_b128 v[234:237], v152 offset:2048
	ds_read_b128 v[238:241], v152 offset:3072
	global_load_lds_dwordx4 v[214:215], off
	v_lshl_add_u64 v[216:217], v[210:211], 0, v[158:159]
	s_add_i32 m0, s10, 0x2000
	s_nop 0
	global_load_lds_dwordx4 v[216:217], off
	s_barrier
	s_waitcnt lgkmcnt(0)
	v_mfma_f32_16x16x32_bf16 v[116:119], v[226:229], v[172:175], v[116:119]
	v_mfma_f32_16x16x32_bf16 v[112:115], v[234:237], v[172:175], v[112:115]
	v_mfma_f32_16x16x32_bf16 v[100:103], v[226:229], v[180:183], v[100:103]
	v_mfma_f32_16x16x32_bf16 v[96:99], v[234:237], v[180:183], v[96:99]
	v_mfma_f32_16x16x32_bf16 v[84:87], v[226:229], v[190:193], v[84:87]
	v_mfma_f32_16x16x32_bf16 v[80:83], v[234:237], v[190:193], v[80:83]
	v_mfma_f32_16x16x32_bf16 v[68:71], v[226:229], v[198:201], v[68:71]
	v_mfma_f32_16x16x32_bf16 v[64:67], v[234:237], v[198:201], v[64:67]
	v_mfma_f32_16x16x32_bf16 v[116:119], v[230:233], v[176:179], v[116:119]
	v_mfma_f32_16x16x32_bf16 v[112:115], v[238:241], v[176:179], v[112:115]
	v_mfma_f32_16x16x32_bf16 v[100:103], v[230:233], v[186:189], v[100:103]
	v_mfma_f32_16x16x32_bf16 v[96:99], v[238:241], v[186:189], v[96:99]
	v_mfma_f32_16x16x32_bf16 v[84:87], v[230:233], v[194:197], v[84:87]
	v_mfma_f32_16x16x32_bf16 v[80:83], v[238:241], v[194:197], v[80:83]
	v_mfma_f32_16x16x32_bf16 v[68:71], v[230:233], v[202:205], v[68:71]
	v_mfma_f32_16x16x32_bf16 v[64:67], v[238:241], v[202:205], v[64:67]
	s_mov_b32 m0, s28
	v_lshl_add_u64 v[218:219], v[154:155], 0, v[156:157]
	s_barrier
	ds_read_b128 v[172:175], v185 offset:16384
	ds_read_b128 v[176:179], v185 offset:17408
	ds_read_b128 v[180:183], v185 offset:18432
	ds_read_b128 v[186:189], v185 offset:19456
	ds_read_b128 v[190:193], v185 offset:20480
	ds_read_b128 v[194:197], v185 offset:21504
	ds_read_b128 v[198:201], v185 offset:22528
	ds_read_b128 v[202:205], v185 offset:23552
	global_load_lds_dwordx4 v[218:219], off
	v_lshl_add_u64 v[220:221], v[154:155], 0, v[158:159]
	s_mov_b32 m0, s29
	s_nop 0
	global_load_lds_dwordx4 v[220:221], off
	s_barrier
	s_waitcnt lgkmcnt(0)
	v_mfma_f32_16x16x32_bf16 v[60:63], v[136:139], v[172:175], v[60:63]
	v_mfma_f32_16x16x32_bf16 v[56:59], v[144:147], v[172:175], v[56:59]
	v_mfma_f32_16x16x32_bf16 v[44:47], v[136:139], v[180:183], v[44:47]
	v_mfma_f32_16x16x32_bf16 v[40:43], v[144:147], v[180:183], v[40:43]
	v_mfma_f32_16x16x32_bf16 v[28:31], v[136:139], v[190:193], v[28:31]
	v_mfma_f32_16x16x32_bf16 v[24:27], v[144:147], v[190:193], v[24:27]
	v_mfma_f32_16x16x32_bf16 v[12:15], v[136:139], v[198:201], v[12:15]
	v_mfma_f32_16x16x32_bf16 v[8:11], v[144:147], v[198:201], v[8:11]
	v_mfma_f32_16x16x32_bf16 v[60:63], v[140:143], v[176:179], v[60:63]
	v_mfma_f32_16x16x32_bf16 v[56:59], v[148:151], v[176:179], v[56:59]
	v_mfma_f32_16x16x32_bf16 v[44:47], v[140:143], v[186:189], v[44:47]
	v_mfma_f32_16x16x32_bf16 v[40:43], v[148:151], v[186:189], v[40:43]
	v_mfma_f32_16x16x32_bf16 v[28:31], v[140:143], v[194:197], v[28:31]
	v_mfma_f32_16x16x32_bf16 v[24:27], v[148:151], v[194:197], v[24:27]
	v_mfma_f32_16x16x32_bf16 v[12:15], v[140:143], v[202:205], v[12:15]
	v_mfma_f32_16x16x32_bf16 v[8:11], v[148:151], v[202:205], v[8:11]
	s_barrier
	v_lshl_add_u64 v[136:137], v[210:211], 0, s[16:17]
	s_add_i32 s8, s8, s71
	v_lshl_add_u64 v[210:211], v[136:137], 0, v[156:157]
	s_mov_b32 m0, s8
	v_lshl_add_u64 v[224:225], v[136:137], 0, v[158:159]
	global_load_lds_dwordx4 v[210:211], off
	s_add_i32 m0, s8, 0x2000
	s_nop 0
	global_load_lds_dwordx4 v[224:225], off
	s_waitcnt vmcnt(6)
	s_barrier
	v_mfma_f32_16x16x32_bf16 v[52:55], v[226:229], v[172:175], v[52:55]
	v_mfma_f32_16x16x32_bf16 v[48:51], v[234:237], v[172:175], v[48:51]
	v_mfma_f32_16x16x32_bf16 v[36:39], v[226:229], v[180:183], v[36:39]
	v_mfma_f32_16x16x32_bf16 v[32:35], v[234:237], v[180:183], v[32:35]
	v_mfma_f32_16x16x32_bf16 v[20:23], v[226:229], v[190:193], v[20:23]
	v_mfma_f32_16x16x32_bf16 v[16:19], v[234:237], v[190:193], v[16:19]
	v_mfma_f32_16x16x32_bf16 v[4:7], v[226:229], v[198:201], v[4:7]
	v_mfma_f32_16x16x32_bf16 v[0:3], v[234:237], v[198:201], v[0:3]
	v_mfma_f32_16x16x32_bf16 v[52:55], v[230:233], v[176:179], v[52:55]
	v_mfma_f32_16x16x32_bf16 v[48:51], v[238:241], v[176:179], v[48:51]
	v_mfma_f32_16x16x32_bf16 v[36:39], v[230:233], v[186:189], v[36:39]
	v_mfma_f32_16x16x32_bf16 v[32:35], v[238:241], v[186:189], v[32:35]
	v_mfma_f32_16x16x32_bf16 v[20:23], v[230:233], v[194:197], v[20:23]
	v_mfma_f32_16x16x32_bf16 v[16:19], v[238:241], v[194:197], v[16:19]
	v_mfma_f32_16x16x32_bf16 v[4:7], v[230:233], v[202:205], v[4:7]
	v_mfma_f32_16x16x32_bf16 v[0:3], v[238:241], v[202:205], v[0:3]
	s_add_i32 s8, 0, 0x18000
	v_add_u32_e32 v148, s8, v184
	s_barrier
	ds_read_b128 v[136:139], v148
	ds_read_b128 v[140:143], v148 offset:1024
	ds_read_b128 v[144:147], v148 offset:2048
	ds_read_b128 v[148:151], v148 offset:3072
	v_lshl_add_u64 v[154:155], v[154:155], 0, s[16:17]
	s_mov_b32 m0, s35
	v_lshl_add_u64 v[226:227], v[154:155], 0, v[156:157]
	ds_read_b128 v[172:175], v185 offset:32768
	ds_read_b128 v[176:179], v185 offset:33792
	ds_read_b128 v[180:183], v185 offset:34816
	ds_read_b128 v[186:189], v185 offset:35840
	ds_read_b128 v[190:193], v185 offset:36864
	ds_read_b128 v[194:197], v185 offset:37888
	ds_read_b128 v[198:201], v185 offset:38912
	ds_read_b128 v[202:205], v185 offset:39936
	global_load_lds_dwordx4 v[226:227], off
	v_lshl_add_u64 v[154:155], v[154:155], 0, v[158:159]
	s_mov_b32 m0, s74
	s_nop 0
	global_load_lds_dwordx4 v[154:155], off
	s_waitcnt lgkmcnt(8)
	s_barrier
	s_waitcnt lgkmcnt(0)
	v_mfma_f32_16x16x32_bf16 v[124:127], v[136:139], v[172:175], v[124:127]
	v_mfma_f32_16x16x32_bf16 v[120:123], v[144:147], v[172:175], v[120:123]
	v_mfma_f32_16x16x32_bf16 v[108:111], v[136:139], v[180:183], v[108:111]
	v_mfma_f32_16x16x32_bf16 v[104:107], v[144:147], v[180:183], v[104:107]
	v_mfma_f32_16x16x32_bf16 v[92:95], v[136:139], v[190:193], v[92:95]
	v_mfma_f32_16x16x32_bf16 v[88:91], v[144:147], v[190:193], v[88:91]
	v_mfma_f32_16x16x32_bf16 v[76:79], v[136:139], v[198:201], v[76:79]
	v_mfma_f32_16x16x32_bf16 v[72:75], v[144:147], v[198:201], v[72:75]
	v_mfma_f32_16x16x32_bf16 v[124:127], v[140:143], v[176:179], v[124:127]
	v_mfma_f32_16x16x32_bf16 v[120:123], v[148:151], v[176:179], v[120:123]
	v_mfma_f32_16x16x32_bf16 v[108:111], v[140:143], v[186:189], v[108:111]
	v_mfma_f32_16x16x32_bf16 v[104:107], v[148:151], v[186:189], v[104:107]
	v_mfma_f32_16x16x32_bf16 v[92:95], v[140:143], v[194:197], v[92:95]
	v_mfma_f32_16x16x32_bf16 v[88:91], v[148:151], v[194:197], v[88:91]
	v_mfma_f32_16x16x32_bf16 v[76:79], v[140:143], v[202:205], v[76:79]
	v_mfma_f32_16x16x32_bf16 v[72:75], v[148:151], v[202:205], v[72:75]
	s_barrier
	s_add_i32 s10, 0, 0x1c000
	s_add_i32 s8, s8, s71
	v_add_u32_e32 v152, s10, v184
	v_lshl_add_u64 v[154:155], v[214:215], 0, s[54:55]
	s_mov_b32 m0, s8
	ds_read_b128 v[226:229], v152
	ds_read_b128 v[230:233], v152 offset:1024
	ds_read_b128 v[234:237], v152 offset:2048
	ds_read_b128 v[238:241], v152 offset:3072
	global_load_lds_dwordx4 v[154:155], off
	v_lshl_add_u64 v[154:155], v[216:217], 0, s[54:55]
	s_add_i32 m0, s8, 0x2000
	s_nop 0
	global_load_lds_dwordx4 v[154:155], off
	s_barrier
	s_waitcnt lgkmcnt(0)
	v_mfma_f32_16x16x32_bf16 v[116:119], v[226:229], v[172:175], v[116:119]
	v_mfma_f32_16x16x32_bf16 v[112:115], v[234:237], v[172:175], v[112:115]
	v_mfma_f32_16x16x32_bf16 v[100:103], v[226:229], v[180:183], v[100:103]
	v_mfma_f32_16x16x32_bf16 v[96:99], v[234:237], v[180:183], v[96:99]
	v_mfma_f32_16x16x32_bf16 v[84:87], v[226:229], v[190:193], v[84:87]
	v_mfma_f32_16x16x32_bf16 v[80:83], v[234:237], v[190:193], v[80:83]
	v_mfma_f32_16x16x32_bf16 v[68:71], v[226:229], v[198:201], v[68:71]
	v_mfma_f32_16x16x32_bf16 v[64:67], v[234:237], v[198:201], v[64:67]
	v_mfma_f32_16x16x32_bf16 v[116:119], v[230:233], v[176:179], v[116:119]
	v_mfma_f32_16x16x32_bf16 v[112:115], v[238:241], v[176:179], v[112:115]
	v_mfma_f32_16x16x32_bf16 v[100:103], v[230:233], v[186:189], v[100:103]
	v_mfma_f32_16x16x32_bf16 v[96:99], v[238:241], v[186:189], v[96:99]
	v_mfma_f32_16x16x32_bf16 v[84:87], v[230:233], v[194:197], v[84:87]
	v_mfma_f32_16x16x32_bf16 v[80:83], v[238:241], v[194:197], v[80:83]
	v_mfma_f32_16x16x32_bf16 v[68:71], v[230:233], v[202:205], v[68:71]
	v_mfma_f32_16x16x32_bf16 v[64:67], v[238:241], v[202:205], v[64:67]
	s_mov_b32 m0, s4
	v_lshl_add_u64 v[154:155], v[218:219], 0, s[54:55]
	s_barrier
	ds_read_b128 v[172:175], v185 offset:49152
	ds_read_b128 v[176:179], v185 offset:50176
	ds_read_b128 v[180:183], v185 offset:51200
	ds_read_b128 v[186:189], v185 offset:52224
	ds_read_b128 v[190:193], v185 offset:53248
	ds_read_b128 v[194:197], v185 offset:54272
	ds_read_b128 v[198:201], v185 offset:55296
	ds_read_b128 v[202:205], v185 offset:56320
	global_load_lds_dwordx4 v[154:155], off
	v_lshl_add_u64 v[154:155], v[220:221], 0, s[54:55]
	s_mov_b32 m0, s5
	s_nop 0
	global_load_lds_dwordx4 v[154:155], off
	s_barrier
	s_waitcnt lgkmcnt(0)
	v_mfma_f32_16x16x32_bf16 v[60:63], v[136:139], v[172:175], v[60:63]
	v_mfma_f32_16x16x32_bf16 v[56:59], v[144:147], v[172:175], v[56:59]
	v_mfma_f32_16x16x32_bf16 v[44:47], v[136:139], v[180:183], v[44:47]
	v_mfma_f32_16x16x32_bf16 v[40:43], v[144:147], v[180:183], v[40:43]
	v_mfma_f32_16x16x32_bf16 v[28:31], v[136:139], v[190:193], v[28:31]
	v_mfma_f32_16x16x32_bf16 v[24:27], v[144:147], v[190:193], v[24:27]
	v_mfma_f32_16x16x32_bf16 v[12:15], v[136:139], v[198:201], v[12:15]
	v_mfma_f32_16x16x32_bf16 v[8:11], v[144:147], v[198:201], v[8:11]
	v_mfma_f32_16x16x32_bf16 v[60:63], v[140:143], v[176:179], v[60:63]
	v_mfma_f32_16x16x32_bf16 v[56:59], v[148:151], v[176:179], v[56:59]
	v_mfma_f32_16x16x32_bf16 v[44:47], v[140:143], v[186:189], v[44:47]
	v_mfma_f32_16x16x32_bf16 v[40:43], v[148:151], v[186:189], v[40:43]
	v_mfma_f32_16x16x32_bf16 v[28:31], v[140:143], v[194:197], v[28:31]
	v_mfma_f32_16x16x32_bf16 v[24:27], v[148:151], v[194:197], v[24:27]
	v_mfma_f32_16x16x32_bf16 v[12:15], v[140:143], v[202:205], v[12:15]
	v_mfma_f32_16x16x32_bf16 v[8:11], v[148:151], v[202:205], v[8:11]
	s_barrier
	s_add_i32 s8, s10, s71
	v_lshl_add_u64 v[136:137], v[210:211], 0, s[54:55]
	s_mov_b32 m0, s8
	s_nop 0
	global_load_lds_dwordx4 v[136:137], off
	v_lshl_add_u64 v[136:137], v[224:225], 0, s[54:55]
	s_add_i32 m0, s8, 0x2000
	s_nop 0
	global_load_lds_dwordx4 v[136:137], off
	s_waitcnt vmcnt(6)
	s_barrier
	v_mfma_f32_16x16x32_bf16 v[52:55], v[226:229], v[172:175], v[52:55]
	v_mfma_f32_16x16x32_bf16 v[48:51], v[234:237], v[172:175], v[48:51]
	v_mfma_f32_16x16x32_bf16 v[36:39], v[226:229], v[180:183], v[36:39]
	v_mfma_f32_16x16x32_bf16 v[32:35], v[234:237], v[180:183], v[32:35]
	v_mfma_f32_16x16x32_bf16 v[20:23], v[226:229], v[190:193], v[20:23]
	v_mfma_f32_16x16x32_bf16 v[16:19], v[234:237], v[190:193], v[16:19]
	v_mfma_f32_16x16x32_bf16 v[4:7], v[226:229], v[198:201], v[4:7]
	v_mfma_f32_16x16x32_bf16 v[0:3], v[234:237], v[198:201], v[0:3]
	v_mfma_f32_16x16x32_bf16 v[52:55], v[230:233], v[176:179], v[52:55]
	v_mfma_f32_16x16x32_bf16 v[48:51], v[238:241], v[176:179], v[48:51]
	v_mfma_f32_16x16x32_bf16 v[36:39], v[230:233], v[186:189], v[36:39]
	v_mfma_f32_16x16x32_bf16 v[32:35], v[238:241], v[186:189], v[32:35]
	v_mfma_f32_16x16x32_bf16 v[20:23], v[230:233], v[194:197], v[20:23]
	v_mfma_f32_16x16x32_bf16 v[16:19], v[238:241], v[194:197], v[16:19]
	v_mfma_f32_16x16x32_bf16 v[4:7], v[230:233], v[202:205], v[4:7]
	v_mfma_f32_16x16x32_bf16 v[0:3], v[238:241], v[202:205], v[0:3]
	v_lshl_add_u64 v[128:129], v[128:129], 0, s[52:53]
	v_lshl_add_u64 v[130:131], v[130:131], 0, s[52:53]
	s_cmp_ge_i32 s9, s12
	s_mov_b32 s8, s9
	s_barrier
	s_cbranch_scc0 .LBB0_588
	s_setprio 0
	v_mov_b32_e32 v191, v206
	s_lshl_b32 s40, s27, 8
	v_readfirstlane_b32 s2, v191
	s_ashr_i32 s26, s2, 2
	s_bfe_u32 s89, s2, 0x20006
	v_bfe_u32 v188, v191, 4, 2
	s_andn2_b32 s26, s26, 63
	v_and_b32_e32 v189, 15, v191
	s_add_i32 s86, s26, s40
	s_lshl_b32 s41, s89, 5
	v_lshlrev_b32_e32 v190, 2, v188
	v_or_b32_e32 v172, s86, v189
	v_or_b32_e32 v187, s41, v190
	v_lshl_or_b32 v186, v188, 3, s41
	s_cmp_lt_i32 s93, 3
	s_mov_b64 s[8:9], -1
	s_cbranch_scc1 .LBB0_1004
	s_cmp_lt_i32 s93, 4
	s_cbranch_scc1 .LBB0_906
	s_cmp_lt_i32 s93, 6
	s_cbranch_scc1 .LBB0_731
	s_cmp_lt_i32 s93, 9
	s_cbranch_scc0 .LBB0_730
	s_cmp_eq_u32 s93, 7
	s_movk_i32 s2, 0x800
	s_cselect_b32 s2, 0x400, s2
	s_cmp_lg_u32 s93, 6
	s_cselect_b32 s2, s2, 0
	v_lshl_or_b32 v174, s14, 8, v186
	v_mov_b64_e32 v[128:129], s[44:45]
	s_movk_i32 s8, 0x1800
	v_mad_i64_i32 v[128:129], s[8:9], v172, s8, v[128:129]
	s_lshl_b32 s2, s2, 1
	v_ashrrev_i32_e32 v175, 31, v174
	v_lshl_add_u64 v[128:129], v[128:129], 0, s[2:3]
	v_lshlrev_b64 v[176:177], 1, v[174:175]
	v_lshl_add_u64 v[128:129], v[128:129], 0, v[176:177]
	v_mov_b64_e32 v[214:215], v[128:129]
	flat_load_dwordx4 v[140:143], v[128:129]
	v_ashrrev_i32_e32 v173, 31, v172
	v_readlane_b32 s8, v254, 43
	v_lshlrev_b64 v[178:179], 11, v[172:173]
	v_readlane_b32 s9, v254, 44
	s_cmp_eq_u32 s93, 8
	s_cselect_b64 s[10:11], -1, 0
	v_lshl_add_u64 v[130:131], s[8:9], 0, v[178:179]
	s_cmp_lg_u32 s93, 8
	v_lshl_add_u64 v[144:145], v[130:131], 0, v[176:177]
	v_mov_b64_e32 v[216:217], v[144:145]
	s_cbranch_scc1 .LBB0_595
	flat_load_dwordx4 v[132:135], v[144:145]
